# v5 + grid barrier: XCD leader releases its local workgroups (XGEN atomic) before its own buffer_inv instead of after
# baseline (speedup 1.0000x reference)
.LBB0_70:
	s_or_b64 exec, exec, s[0:1]
	s_mov_b64 s[0:1], exec
	v_mbcnt_lo_u32_b32 v1, s0, 0
	v_mbcnt_hi_u32_b32 v1, s1, v1
	v_cmp_eq_u32_e32 vcc, 0, v1
	s_waitcnt vmcnt(0)
	s_and_saveexec_b64 s[10:11], vcc
	s_cbranch_execz .LBB0_72
	s_bcnt1_i32_b64 s0, s[0:1]
	v_mov_b32_e32 v1, 0x2000
	v_mov_b32_e32 v2, s0
	global_atomic_add v1, v2, s[8:9] offset:1024
.LBB0_72:
	s_or_b64 exec, exec, s[10:11]
	buffer_inv sc1
	s_waitcnt vmcnt(0)

.LBB0_317:
	s_or_b64 exec, exec, s[0:1]
	s_mov_b64 s[0:1], exec
	v_mbcnt_lo_u32_b32 v1, s0, 0
	v_mbcnt_hi_u32_b32 v1, s1, v1
	v_cmp_eq_u32_e32 vcc, 0, v1
	s_waitcnt vmcnt(0)
	s_and_saveexec_b64 s[12:13], vcc
	s_cbranch_execz .LBB0_319
	s_bcnt1_i32_b64 s0, s[0:1]
	v_mov_b32_e32 v1, 0x2000
	v_mov_b32_e32 v2, s0
	global_atomic_add v1, v2, s[8:9] offset:1024
.LBB0_319:
	s_or_b64 exec, exec, s[12:13]
	buffer_inv sc1
	s_waitcnt vmcnt(0)

.LBB0_322:
	s_or_b64 exec, exec, s[10:11]
	s_waitcnt vmcnt(0)
	global_atomic_add v[180:181], v229, off
	buffer_inv sc1
	s_waitcnt vmcnt(0)

.LBB0_856:
	s_or_b64 exec, exec, s[0:1]
	s_waitcnt vmcnt(0)
	global_atomic_add v[180:181], v225, off
	buffer_inv sc1
	s_waitcnt vmcnt(0)
